# hgrn pass 3 step 4: LDS reads of V column, q-tilde, masked scores, decay and k' tiles issued ahead of their MFMAs with counted lgkmcnt (was 17 dependent LDS round trips)
# speedup vs baseline: 1.0460x; 1.0036x over previous
.LBB0_415:
	s_add_i32 s4, s88, s4
	s_waitcnt lgkmcnt(0)
	s_barrier
	v_add3_u32 v47, s4, v76, v96
	ds_read_u16 v166, v47
	ds_read_u16 v167, v47 offset:264
	ds_read_u16 v168, v47 offset:528
	ds_read_u16 v169, v47 offset:792
	ds_read_u16 v170, v47 offset:1056
	ds_read_u16 v171, v47 offset:1320
	ds_read_u16 v172, v47 offset:1584
	ds_read_u16 v173, v47 offset:1848
	v_add_u32_e32 v101, 0xc000, v89
	v_add_u32_e32 v122, 0xd000, v89
	ds_read2_b64 v[174:177], v101 offset1:4
	ds_read2_b64 v[178:181], v122 offset0:32 offset1:36
	ds_read2_b64 v[182:185], v101 offset0:8 offset1:12
	ds_read2_b64 v[186:189], v122 offset0:40 offset1:44
	s_add_i32 s6, s6, 1
	s_add_i32 s4, s5, s6
	v_add_u32_e32 v99, 32, v99
	v_subrev_u32_e32 v100, 32, v100
	v_add_u32_e32 v251, 0x18600, v50
	v_add_u32_e32 v250, v79, v77
	s_cmp_eq_u32 s4, 1
	v_cvt_pk_bf16_f32 v110, v16, v17
	v_cvt_pk_bf16_f32 v111, v18, v19
	v_cvt_pk_bf16_f32 v112, v12, v13
	v_cvt_pk_bf16_f32 v113, v14, v15
	s_waitcnt lgkmcnt(4)
	v_lshl_or_b32 v44, v167, 16, v166
	v_lshl_or_b32 v45, v169, 16, v168
	v_lshl_or_b32 v46, v171, 16, v170
	v_lshl_or_b32 v47, v173, 16, v172
	ds_read2_b64 v[190:193], v101 offset0:16 offset1:20
	ds_read2_b64 v[206:209], v122 offset0:48 offset1:52
	ds_read2_b64 v[210:213], v101 offset0:24 offset1:28
	ds_read2_b64 v[214:217], v122 offset0:56 offset1:60
	ds_read_b128 v[218:221], v78
	ds_read_b128 v[222:225], v78 offset:1280
	s_waitcnt lgkmcnt(9)
	v_mfma_f32_16x16x32_bf16 v[106:109], v[174:177], v[110:113], 0
	s_waitcnt lgkmcnt(8)
	v_mfma_f32_16x16x32_bf16 v[102:105], v[178:181], v[110:113], 0
	v_cvt_pk_bf16_f32 v110, v24, v25
	v_cvt_pk_bf16_f32 v111, v26, v27
	v_cvt_pk_bf16_f32 v112, v20, v21
	v_cvt_pk_bf16_f32 v113, v22, v23
	ds_read_b128 v[226:229], v251
	ds_read_b128 v[230:233], v251 offset:64
	ds_read_b128 v[234:237], v251 offset:128
	ds_read_b128 v[238:241], v251 offset:192
	s_waitcnt lgkmcnt(11)
	v_mfma_f32_16x16x32_bf16 v[106:109], v[182:185], v[110:113], v[106:109]
	s_waitcnt lgkmcnt(10)
	v_mfma_f32_16x16x32_bf16 v[102:105], v[186:189], v[110:113], v[102:105]
	v_cvt_pk_bf16_f32 v110, v32, v33
	v_cvt_pk_bf16_f32 v111, v34, v35
	v_cvt_pk_bf16_f32 v112, v28, v29
	v_cvt_pk_bf16_f32 v113, v30, v31
	ds_read_b128 v[242:245], v251 offset:256
	ds_read_b128 v[246:249], v251 offset:320
	ds_read_b128 v[114:117], v251 offset:384
	ds_read_b128 v[118:121], v251 offset:448
	s_waitcnt lgkmcnt(13)
	v_mfma_f32_16x16x32_bf16 v[106:109], v[190:193], v[110:113], v[106:109]
	s_waitcnt lgkmcnt(12)
	v_mfma_f32_16x16x32_bf16 v[102:105], v[206:209], v[110:113], v[102:105]
	v_cvt_pk_bf16_f32 v110, v36, v37
	v_cvt_pk_bf16_f32 v111, v38, v39
	v_cvt_pk_bf16_f32 v112, v40, v41
	v_cvt_pk_bf16_f32 v113, v42, v43
	ds_read_b128 v[174:177], v250
	ds_read_b128 v[178:181], v250 offset:1280
	s_waitcnt lgkmcnt(13)
	v_mfma_f32_16x16x32_bf16 v[106:109], v[210:213], v[110:113], v[106:109]
	s_waitcnt lgkmcnt(12)
	v_mfma_f32_16x16x32_bf16 v[102:105], v[214:217], v[110:113], v[102:105]
	ds_read_b128 v[182:185], v250 offset:2560
	ds_read_b128 v[186:189], v97
	s_waitcnt lgkmcnt(12)
	v_mfma_f32_16x16x32_bf16 v[102:105], v[222:225], v[44:47], v[102:105]
	v_mfma_f32_16x16x32_bf16 v[106:109], v[218:221], v[44:47], v[106:109]
	ds_read_b128 v[190:193], v250 offset:5120
	ds_read_b128 v[206:209], v250 offset:6400
	s_waitcnt lgkmcnt(5)
	v_pk_mul_f32 v[16:17], v[16:17], v[226:227]
	v_pk_mul_f32 v[18:19], v[18:19], v[228:229]
	ds_read_b128 v[210:213], v250 offset:7680
	ds_read_b128 v[214:217], v98
	v_mfma_f32_16x16x32_bf16 v[16:19], v[174:177], v[44:47], v[16:19]
	s_waitcnt lgkmcnt(6)
	v_pk_mul_f32 v[12:13], v[12:13], v[230:231]
	v_pk_mul_f32 v[14:15], v[14:15], v[232:233]
	v_add_u32_e32 v205, 0x2000, v90
	v_add_u32_e32 v250, 0x400, v90
	v_add_u32_e32 v251, 0x2400, v90
	v_mfma_f32_16x16x32_bf16 v[12:15], v[178:181], v[44:47], v[12:15]
	ds_write2_b32 v205, v102, v103 offset0:64 offset1:196
	ds_write2_b32 v250, v108, v109 offset0:8 offset1:140
	ds_write2_b32 v251, v104, v105 offset0:72 offset1:204
	ds_write2_b32 v90, v106, v107 offset1:132
	s_waitcnt lgkmcnt(9)
	v_pk_mul_f32 v[24:25], v[24:25], v[234:235]
	v_pk_mul_f32 v[26:27], v[26:27], v[236:237]
	s_nop 1
	v_mfma_f32_16x16x32_bf16 v[24:27], v[182:185], v[44:47], v[24:27]
	s_waitcnt lgkmcnt(8)
	v_pk_mul_f32 v[20:21], v[20:21], v[238:239]
	v_pk_mul_f32 v[22:23], v[22:23], v[240:241]
	s_nop 1
	v_mfma_f32_16x16x32_bf16 v[20:23], v[186:189], v[44:47], v[20:23]
	s_waitcnt lgkmcnt(7)
	v_pk_mul_f32 v[32:33], v[32:33], v[242:243]
	v_pk_mul_f32 v[34:35], v[34:35], v[244:245]
	s_nop 1
	v_mfma_f32_16x16x32_bf16 v[32:35], v[190:193], v[44:47], v[32:35]
	s_waitcnt lgkmcnt(6)
	v_pk_mul_f32 v[28:29], v[28:29], v[246:247]
	v_pk_mul_f32 v[30:31], v[30:31], v[248:249]
	s_nop 1
	v_mfma_f32_16x16x32_bf16 v[28:31], v[206:209], v[44:47], v[28:31]
	s_waitcnt lgkmcnt(5)
	v_pk_mul_f32 v[36:37], v[36:37], v[114:115]
	v_pk_mul_f32 v[38:39], v[38:39], v[116:117]
	s_nop 1
	v_mfma_f32_16x16x32_bf16 v[36:39], v[210:213], v[44:47], v[36:39]
	s_waitcnt lgkmcnt(0)
	v_pk_mul_f32 v[40:41], v[40:41], v[118:119]
	v_pk_mul_f32 v[42:43], v[42:43], v[120:121]
	s_nop 1
	v_mfma_f32_16x16x32_bf16 v[40:43], v[214:217], v[44:47], v[40:43]
	s_cbranch_scc1 .LBB0_424
